# LayerNorm rows remapped to the GEMM tile owner group (WG c normalises 64 rows of row-block pm(c)), on top of v52
# baseline (speedup 1.0000x reference)
.LBB0_1958:
	s_andn2_b64 vcc, exec, s[8:9]
	s_cbranch_vccnz .LBB0_2034
	s_mov_b32 s0, s80
	s_mov_b32 s2, -1
	s_mov_b64 s[8:9], s[96:97]
	v_mbcnt_lo_u32_b32 v0, s2, 0
	v_mbcnt_hi_u32_b32 v0, s2, v0
	v_readlane_b32 s99, v250, 7
	s_cmp_lg_u32 s94, 0x100
	s_cbranch_scc1 .Lmy_lnmap_a
	s_and_b32 s98, s99, 7
	s_lshl_b32 s98, s98, 3
	s_bfe_u32 s2, s99, 0x30003
	s_or_b32 s98, s98, s2
	s_lshl_b32 s98, s98, 2
	s_lshr_b32 s99, s99, 6
	s_or_b32 s99, s99, s98
.Lmy_lnmap_a:
	s_lshl_b32 s2, s99, 3
	s_add_i32 s2, s0, s2
	s_mov_b64 s[12:13], s[96:97]
	s_mov_b64 s[16:17], s[96:97]
	s_mov_b64 s[20:21], s[96:97]
	s_mov_b64 s[18:19], s[96:97]
	s_cmpk_gt_i32 s2, 0x7ff
	s_cbranch_scc1 .LBB0_1978
	s_load_dwordx2 s[20:21], s[20:21], 0x110
	s_nop 0
	s_load_dwordx2 s[8:9], s[8:9], 0x110
	s_nop 0
	s_load_dwordx2 s[22:23], s[12:13], 0x10
	s_nop 0
	s_load_dwordx2 s[16:17], s[16:17], 0x18
	s_nop 0
	s_load_dwordx2 s[18:19], s[18:19], 0x110
	s_waitcnt lgkmcnt(0)
	s_add_u32 s12, s20, 0x900000
	s_addc_u32 s13, s21, 0
	s_lshl_b32 s10, s48, 12
	s_lshl_b64 s[26:27], s[10:11], 2
	s_add_u32 s16, s16, s26
	s_addc_u32 s17, s17, s27
	s_add_u32 s22, s22, s26
	s_addc_u32 s23, s23, s27
	s_lshl_b32 s36, s2, 3
	v_lshlrev_b32_e32 v2, 3, v0
	s_cmp_lg_u64 s[20:21], 0
	v_ashrrev_i32_e32 v3, 31, v2
	s_cselect_b64 s[2:3], -1, 0
	v_cmp_eq_u32_e32 vcc, 0, v0
	v_lshlrev_b64 v[4:5], 2, v[2:3]
	s_and_b64 s[42:43], vcc, s[2:3]
	s_lshl_b32 s98, s80, 10
	v_lshl_add_u32 v194, v0, 4, s98
	global_load_dwordx4 v[196:199], v194, s[22:23]
	global_load_dwordx4 v[200:203], v194, s[16:17]
	v_lshlrev_b32_e32 v195, 5, v0
	s_waitcnt vmcnt(0)
	ds_write_b128 v194, v[196:199]
	ds_write_b128 v194, v[200:203] offset:8192
	s_waitcnt lgkmcnt(0)
	s_barrier
	v_lshl_add_u64 v[116:117], s[22:23], 0, v[4:5]
	v_lshl_add_u64 v[118:119], s[16:17], 0, v[4:5]
	s_mov_b64 s[2:3], 0x1000
	v_ashrrev_i32_e32 v1, 31, v0
	v_lshl_add_u64 v[120:121], v[116:117], 0, s[2:3]
	v_lshl_add_u64 v[122:123], v[118:119], 0, s[2:3]
	s_mov_b64 s[2:3], 0x1800
	s_lshl_b32 s0, s0, 4
	s_ashr_i32 s37, s36, 31
	v_lshl_add_u64 v[124:125], v[116:117], 0, s[2:3]
	v_lshl_add_u64 v[126:127], v[118:119], 0, s[2:3]
	s_lshl_b32 s44, s99, 7
	s_add_i32 s44, s44, s0
	s_lshl_b64 s[46:47], s[36:37], 12
	v_lshl_add_u64 v[128:129], v[2:3], 1, s[18:19]
	v_lshl_add_u64 v[130:131], v[0:1], 4, s[8:9]
	s_branch .LBB0_1962

.Lmy_lnmap_b:
	s_lshl_b32 s2, s99, 3
	s_add_i32 s2, s0, s2
	s_mov_b64 s[12:13], s[96:97]
	s_mov_b64 s[16:17], s[96:97]
	s_mov_b64 s[20:21], s[96:97]
	s_mov_b64 s[18:19], s[96:97]
	s_cmpk_gt_i32 s2, 0x7ff
	s_cbranch_scc1 .LBB0_2327
	s_load_dwordx2 s[20:21], s[20:21], 0x110
	s_nop 0
	s_load_dwordx2 s[8:9], s[8:9], 0x110
	s_nop 0
	s_load_dwordx2 s[22:23], s[12:13], 0x10
	s_nop 0
	s_load_dwordx2 s[16:17], s[16:17], 0x18
	s_nop 0
	s_load_dwordx2 s[18:19], s[18:19], 0x110
	s_waitcnt lgkmcnt(0)
	s_add_u32 s12, s20, 0x920000
	s_addc_u32 s13, s21, 0
	s_lshl_b32 s3, s48, 12
	s_or_b32 s10, s3, 0x800
	s_lshl_b64 s[20:21], s[10:11], 2
	s_add_u32 s16, s16, s20
	s_addc_u32 s17, s17, s21
	v_lshlrev_b32_e32 v2, 3, v0
	s_add_u32 s20, s22, s20
	v_ashrrev_i32_e32 v3, 31, v2
	s_addc_u32 s21, s23, s21
	s_lshl_b32 s36, s2, 3
	v_lshlrev_b64 v[4:5], 2, v[2:3]
	s_mov_b64 s[2:3], 0x1000
	v_lshl_add_u64 v[6:7], v[4:5], 0, s[2:3]
	s_mov_b64 s[2:3], 0x1800
	v_ashrrev_i32_e32 v1, 31, v0
	s_lshl_b32 s98, s80, 10
	v_lshl_add_u32 v194, v0, 4, s98
	global_load_dwordx4 v[196:199], v194, s[20:21]
	global_load_dwordx4 v[200:203], v194, s[16:17]
	v_lshlrev_b32_e32 v195, 5, v0
	s_waitcnt vmcnt(0)
	ds_write_b128 v194, v[196:199]
	ds_write_b128 v194, v[200:203] offset:8192
	s_waitcnt lgkmcnt(0)
	s_barrier
	v_lshl_add_u64 v[116:117], s[20:21], 0, v[4:5]
	v_lshl_add_u64 v[118:119], s[16:17], 0, v[4:5]
	v_lshl_add_u64 v[4:5], v[4:5], 0, s[2:3]
	s_lshl_b32 s0, s0, 4
	s_ashr_i32 s37, s36, 31
	v_cmp_eq_u32_e64 s[40:41], 0, v0
	v_lshl_add_u64 v[120:121], s[20:21], 0, v[6:7]
	v_lshl_add_u64 v[122:123], s[16:17], 0, v[6:7]
	v_lshl_add_u64 v[124:125], s[20:21], 0, v[4:5]
	v_lshl_add_u64 v[126:127], s[16:17], 0, v[4:5]
	s_lshl_b32 s44, s99, 7
	s_add_i32 s44, s44, s0
	s_lshl_b64 s[46:47], s[36:37], 12
	v_lshl_add_u64 v[128:129], v[2:3], 1, s[18:19]
	v_lshl_add_u64 v[130:131], v[0:1], 4, s[8:9]
	s_branch .LBB0_2311
